# previous + ffn1 k-loop rewritten: BK=32 LDS ping-pong, register-staged loads 2 stages ahead, ds_writes interleaved with MFMAs, pipelined fragment reads
# speedup vs baseline: 1.0267x; 1.0222x over previous
; DI int ltid() { int t = __builtin_amdgcn_workitem_id_x(); asm volatile("" : "+v"(t)); return t; }
; DI void kloopT(f32x16 (&acc)[2][2], const u16* A, int lda, const u16* B, int ldb, int K, char* smem) { gemm_kloop(acc, A, lda, B, ldb, K, smem); }
; DI void kloopT(f32x16 (&acc)[4][2], const u16* A, int lda, const u16* B, int ldb, int K, char* smem) { gemm_kloop4(acc, A, lda, B, ldb, K, smem); }
; DI void gemm_kloop4(f32x16 (&acc)[4][2], const u16* __restrict__ A, int lda, const u16* __restrict__ B, int ldb, int K,
;                     char* smem) {
;   const int tid = ltid(), lane = tid & 63, wid = tid >> 6, wr = wid >> 1, wc = wid & 1;
;   const int lr = tid >> 3, lc = tid & 7;
;   const int r = lane & 31, h5 = lane >> 5;
;   u32x4 ra[8], rb[4];
;   const int nk = K >> 6;
;   const u16* Ap = A + (size_t)lr * lda + lc * 8;
;   const u16* Bp = B + (size_t)lr * ldb + lc * 8;
;   const int woff = lr * 128 + ((lc ^ ((lr >> 1) & 7)) << 4);
;   const int sw = (r >> 1) & 7;
;   const int aoff = (wr * 128 + r) * 128, boff = 32768 + (wc * 64 + r) * 128;
; #pragma unroll
;   for (int i = 0; i < 8; ++i) ra[i] = *(const u32x4*)(Ap + (size_t)(32 * i) * lda);
; #pragma unroll
;   for (int i = 0; i < 4; ++i) rb[i] = *(const u32x4*)(Bp + (size_t)(32 * i) * ldb);
;   __syncthreads();
; #pragma unroll
;   for (int i = 0; i < 8; ++i) *(u32x4*)(smem + woff + i * 4096) = ra[i];
; #pragma unroll
;   for (int i = 0; i < 4; ++i) *(u32x4*)(smem + 32768 + woff + i * 4096) = rb[i];
;   __syncthreads();
; template <int MTW> DI void gemm_ffn1_phase(const Params& p, int mrows, int bid, int nb, char* smem) {
;     ...
;   for (int t = bid; t < ntiles; t += nb) {
;     const int row0 = (t / 44) * (64 * MTW), col0 = (t % 44) * 128;
;     f32x16 acc[MTW][2];
;     zero_accT<MTW>(acc);
;     kloopT(acc, H + (size_t)row0 * 1024, 1024, WT + (size_t)col0 * 1024, 1024, 1024, smem);
.LBB0_61:
	s_mul_hi_i32 s9, s34, 0x2e8ba2e9
	s_lshr_b32 s28, s9, 31
	s_ashr_i32 s9, s9, 3
	s_add_i32 s9, s9, s28
	s_lshl_b32 s28, s9, 8
	s_mul_i32 s9, s9, 44
	s_sub_i32 s9, s34, s9
	s_ashr_i32 s29, s28, 31
	v_mov_b32_e32 v14, v196
	s_lshl_b32 s38, s9, 7
	v_lshrrev_b32_e32 v0, 2, v196
	v_and_b32_e32 v240, 3, v196
	v_lshlrev_b32_e32 v241, 4, v240
	v_mul_u32_u24_e32 v179, 2048, v0
	v_add_u32_e32 v179, v179, v241
	v_add_u32_e32 v180, 131072, v179
	v_add_u32_e32 v181, 262144, v179
	v_add_u32_e32 v182, 393216, v179
	v_mul_u32_u24_e32 v183, 2048, v0
	v_add_u32_e32 v183, v183, v241
	v_add_u32_e32 v184, 131072, v183
	v_bfe_u32 v241, v196, 4, 2
	v_xor_b32_e32 v241, v241, v240
	v_lshlrev_b32_e32 v241, 4, v241
	v_lshl_add_u32 v185, v0, 6, v241
	v_and_b32_e32 v0, 31, v196
	v_bfe_u32 v240, v196, 5, 1
	v_bfe_u32 v241, v196, 2, 2
	v_xor_b32_e32 v240, v240, v241
	v_lshlrev_b32_e32 v240, 4, v240
	v_bfe_u32 v241, v196, 7, 1
	v_lshl_add_u32 v241, v241, 7, v0
	v_lshl_add_u32 v186, v241, 6, v240
	v_xor_b32_e32 v187, 32, v186
	v_bfe_u32 v241, v196, 6, 1
	v_lshl_add_u32 v241, v241, 6, v0
	v_lshl_add_u32 v188, v241, 6, v240
	v_add_u32_e32 v188, 16384, v188
	v_xor_b32_e32 v189, 32, v188
	s_mul_i32 s45, s28, 2048
	s_mul_hi_u32 s46, s28, 2048
	s_add_u32 s40, s6, s45
	s_addc_u32 s41, s7, s46
	s_mul_i32 s45, s38, 2048
	s_mul_hi_u32 s46, s38, 2048
	s_add_u32 s42, s14, s45
	s_addc_u32 s43, s15, s46
	global_load_dwordx4 v[130:133], v179, s[40:41]
	global_load_dwordx4 v[134:137], v180, s[40:41]
	global_load_dwordx4 v[138:141], v181, s[40:41]
	global_load_dwordx4 v[142:145], v182, s[40:41]
	global_load_dwordx4 v[146:149], v183, s[42:43]
	global_load_dwordx4 v[150:153], v184, s[42:43]
	s_add_u32 s40, s40, 64
	s_addc_u32 s41, s41, 0
	s_add_u32 s42, s42, 64
	s_addc_u32 s43, s43, 0
	global_load_dwordx4 v[154:157], v179, s[40:41]
	global_load_dwordx4 v[158:161], v180, s[40:41]
	global_load_dwordx4 v[162:165], v181, s[40:41]
	global_load_dwordx4 v[166:169], v182, s[40:41]
	global_load_dwordx4 v[170:173], v183, s[42:43]
	global_load_dwordx4 v[174:177], v184, s[42:43]
	s_add_u32 s40, s40, 64
	s_addc_u32 s41, s41, 0
	s_add_u32 s42, s42, 64
	s_addc_u32 s43, s43, 0
	v_mov_b64_e32 v[114:115], 0
	v_mov_b64_e32 v[116:117], 0
	v_mov_b64_e32 v[118:119], 0
	v_mov_b64_e32 v[120:121], 0
	v_mov_b64_e32 v[122:123], 0
	v_mov_b64_e32 v[124:125], 0
	v_mov_b64_e32 v[126:127], 0
	v_mov_b64_e32 v[128:129], 0
	v_mov_b64_e32 v[98:99], 0
	v_mov_b64_e32 v[100:101], 0
	v_mov_b64_e32 v[102:103], 0
	v_mov_b64_e32 v[104:105], 0
	v_mov_b64_e32 v[106:107], 0
	v_mov_b64_e32 v[108:109], 0
	v_mov_b64_e32 v[110:111], 0
	v_mov_b64_e32 v[112:113], 0
	v_mov_b64_e32 v[82:83], 0
	v_mov_b64_e32 v[84:85], 0
	v_mov_b64_e32 v[86:87], 0
	v_mov_b64_e32 v[88:89], 0
	v_mov_b64_e32 v[90:91], 0
	v_mov_b64_e32 v[92:93], 0
	v_mov_b64_e32 v[94:95], 0
	v_mov_b64_e32 v[96:97], 0
	v_mov_b64_e32 v[66:67], 0
	v_mov_b64_e32 v[68:69], 0
	v_mov_b64_e32 v[70:71], 0
	v_mov_b64_e32 v[72:73], 0
	v_mov_b64_e32 v[74:75], 0
	v_mov_b64_e32 v[76:77], 0
	v_mov_b64_e32 v[78:79], 0
	v_mov_b64_e32 v[80:81], 0
	v_mov_b64_e32 v[50:51], 0
	v_mov_b64_e32 v[52:53], 0
	v_mov_b64_e32 v[54:55], 0
	v_mov_b64_e32 v[56:57], 0
	v_mov_b64_e32 v[58:59], 0
	v_mov_b64_e32 v[60:61], 0
	v_mov_b64_e32 v[62:63], 0
	v_mov_b64_e32 v[64:65], 0
	v_mov_b64_e32 v[34:35], 0
	v_mov_b64_e32 v[36:37], 0
	v_mov_b64_e32 v[38:39], 0
	v_mov_b64_e32 v[40:41], 0
	v_mov_b64_e32 v[42:43], 0
	v_mov_b64_e32 v[44:45], 0
	v_mov_b64_e32 v[46:47], 0
	v_mov_b64_e32 v[48:49], 0
	v_mov_b64_e32 v[18:19], 0
	v_mov_b64_e32 v[20:21], 0
	v_mov_b64_e32 v[22:23], 0
	v_mov_b64_e32 v[24:25], 0
	v_mov_b64_e32 v[26:27], 0
	v_mov_b64_e32 v[28:29], 0
	v_mov_b64_e32 v[30:31], 0
	v_mov_b64_e32 v[32:33], 0
	v_mov_b64_e32 v[2:3], 0
	v_mov_b64_e32 v[4:5], 0
	v_mov_b64_e32 v[6:7], 0
	v_mov_b64_e32 v[8:9], 0
	v_mov_b64_e32 v[10:11], 0
	v_mov_b64_e32 v[12:13], 0
	v_mov_b64_e32 v[14:15], 0
	v_mov_b64_e32 v[16:17], 0
	s_barrier
	s_waitcnt vmcnt(11)
	ds_write_b128 v185, v[130:133] offset:0
	s_waitcnt vmcnt(10)
	ds_write_b128 v185, v[134:137] offset:4096
	s_waitcnt vmcnt(9)
	ds_write_b128 v185, v[138:141] offset:8192
	s_waitcnt vmcnt(8)
	ds_write_b128 v185, v[142:145] offset:12288
	s_waitcnt vmcnt(7)
	ds_write_b128 v185, v[146:149] offset:16384
	s_waitcnt vmcnt(6)
	ds_write_b128 v185, v[150:153] offset:20480
	s_waitcnt lgkmcnt(0)
	s_barrier
	s_mov_b32 s44, 0
; #define MFMA32(a, b, c) __builtin_amdgcn_mfma_f32_32x32x16_bf16((a), (b), (c), 0, 0, 0)
; DI void gemm_kloop4(f32x16 (&acc)[4][2], const u16* __restrict__ A, int lda, const u16* __restrict__ B, int ldb, int K,
;                     char* smem) {
;     ...
; #pragma unroll 1
;   for (int kt = 0; kt < nk; ++kt) {
;     if (kt + 1 < nk) {
; #pragma unroll
;       for (int i = 0; i < 8; ++i) ra[i] = *(const u32x4*)(Ap + (size_t)(32 * i) * lda + (kt + 1) * 64);
; #pragma unroll
;       for (int i = 0; i < 4; ++i) rb[i] = *(const u32x4*)(Bp + (size_t)(32 * i) * ldb + (kt + 1) * 64);
;     }
;     __builtin_amdgcn_s_setprio(1);
; #pragma unroll
;     for (int s = 0; s < 4; ++s) {
;       const int ch = ((2 * s + h5) ^ sw) << 4;
;       const bf16x8 b0 = *(const bf16x8*)(smem + boff + ch);
;       const bf16x8 b1 = *(const bf16x8*)(smem + boff + 4096 + ch);
; #pragma unroll
;       for (int mt = 0; mt < 4; ++mt) {
;         const bf16x8 a = *(const bf16x8*)(smem + aoff + mt * 4096 + ch);
;         acc[mt][0] = MFMA32(a, b0, acc[mt][0]);
;         acc[mt][1] = MFMA32(a, b1, acc[mt][1]);
;       }
;     }
;     __builtin_amdgcn_s_setprio(0);
;     __syncthreads();
;     if (kt + 1 < nk) {
; #pragma unroll
;       for (int i = 0; i < 8; ++i) *(u32x4*)(smem + woff + i * 4096) = ra[i];
; #pragma unroll
;       for (int i = 0; i < 4; ++i) *(u32x4*)(smem + 32768 + woff + i * 4096) = rb[i];
;     }
;     __syncthreads();
;   }
.Lg_ffn1_loop:
	global_load_dwordx4 v[130:133], v179, s[40:41]
	global_load_dwordx4 v[134:137], v180, s[40:41]
	global_load_dwordx4 v[138:141], v181, s[40:41]
	global_load_dwordx4 v[142:145], v182, s[40:41]
	global_load_dwordx4 v[146:149], v183, s[42:43]
	global_load_dwordx4 v[150:153], v184, s[42:43]
	s_add_u32 s40, s40, 64
	s_addc_u32 s41, s41, 0
	s_add_u32 s42, s42, 64
	s_addc_u32 s43, s43, 0
	ds_read_b128 v[190:193], v188 offset:0
	ds_read_b128 v[208:211], v186 offset:0
	ds_read_b128 v[212:215], v188 offset:2048
	ds_read_b128 v[216:219], v186 offset:2048
	ds_read_b128 v[220:223], v186 offset:4096
	ds_read_b128 v[224:227], v186 offset:6144
	ds_read_b128 v[228:231], v189 offset:0
	ds_read_b128 v[232:235], v187 offset:0
	ds_read_b128 v[236:239], v189 offset:2048
	ds_read_b128 v[248:251], v187 offset:2048
	ds_read_b128 v[252:255], v187 offset:4096
	s_waitcnt lgkmcnt(9)
	v_mfma_f32_32x32x16_bf16 v[114:129], v[208:211], v[190:193], v[114:129]
	s_waitcnt lgkmcnt(8)
	v_mfma_f32_32x32x16_bf16 v[98:113], v[208:211], v[212:215], v[98:113]
	ds_read_b128 v[208:211], v187 offset:6144
	s_waitcnt lgkmcnt(8)
	v_mfma_f32_32x32x16_bf16 v[82:97], v[216:219], v[190:193], v[82:97]
	s_waitcnt lgkmcnt(8)
	v_mfma_f32_32x32x16_bf16 v[66:81], v[216:219], v[212:215], v[66:81]
	s_waitcnt vmcnt(11)
	ds_write_b128 v185, v[154:157] offset:24576
	s_waitcnt lgkmcnt(8)
	v_mfma_f32_32x32x16_bf16 v[50:65], v[220:223], v[190:193], v[50:65]
	s_waitcnt lgkmcnt(8)
	v_mfma_f32_32x32x16_bf16 v[34:49], v[220:223], v[212:215], v[34:49]
	s_waitcnt vmcnt(10)
	ds_write_b128 v185, v[158:161] offset:28672
	s_waitcnt lgkmcnt(8)
	v_mfma_f32_32x32x16_bf16 v[18:33], v[224:227], v[190:193], v[18:33]
	s_waitcnt lgkmcnt(8)
	v_mfma_f32_32x32x16_bf16 v[2:17], v[224:227], v[212:215], v[2:17]
	s_waitcnt vmcnt(9)
	ds_write_b128 v185, v[162:165] offset:32768
	s_waitcnt lgkmcnt(7)
	v_mfma_f32_32x32x16_bf16 v[114:129], v[232:235], v[228:231], v[114:129]
	s_waitcnt lgkmcnt(6)
	v_mfma_f32_32x32x16_bf16 v[98:113], v[232:235], v[236:239], v[98:113]
	s_waitcnt vmcnt(8)
	ds_write_b128 v185, v[166:169] offset:36864
	s_waitcnt lgkmcnt(6)
	v_mfma_f32_32x32x16_bf16 v[82:97], v[248:251], v[228:231], v[82:97]
	s_waitcnt lgkmcnt(6)
	v_mfma_f32_32x32x16_bf16 v[66:81], v[248:251], v[236:239], v[66:81]
	s_waitcnt vmcnt(7)
	ds_write_b128 v185, v[170:173] offset:40960
	s_waitcnt lgkmcnt(6)
	v_mfma_f32_32x32x16_bf16 v[50:65], v[252:255], v[228:231], v[50:65]
	s_waitcnt lgkmcnt(6)
	v_mfma_f32_32x32x16_bf16 v[34:49], v[252:255], v[236:239], v[34:49]
	s_waitcnt vmcnt(6)
	ds_write_b128 v185, v[174:177] offset:45056
	s_waitcnt lgkmcnt(6)
	v_mfma_f32_32x32x16_bf16 v[18:33], v[208:211], v[228:231], v[18:33]
	s_waitcnt lgkmcnt(6)
	v_mfma_f32_32x32x16_bf16 v[2:17], v[208:211], v[236:239], v[2:17]
	s_waitcnt lgkmcnt(0)
	s_barrier
	global_load_dwordx4 v[154:157], v179, s[40:41]
	global_load_dwordx4 v[158:161], v180, s[40:41]
	global_load_dwordx4 v[162:165], v181, s[40:41]
	global_load_dwordx4 v[166:169], v182, s[40:41]
	global_load_dwordx4 v[170:173], v183, s[42:43]
	global_load_dwordx4 v[174:177], v184, s[42:43]
	s_add_u32 s40, s40, 64
	s_addc_u32 s41, s41, 0
	s_add_u32 s42, s42, 64
	s_addc_u32 s43, s43, 0
	ds_read_b128 v[190:193], v188 offset:24576
	ds_read_b128 v[208:211], v186 offset:24576
	ds_read_b128 v[212:215], v188 offset:26624
	ds_read_b128 v[216:219], v186 offset:26624
	ds_read_b128 v[220:223], v186 offset:28672
	ds_read_b128 v[224:227], v186 offset:30720
	ds_read_b128 v[228:231], v189 offset:24576
	ds_read_b128 v[232:235], v187 offset:24576
	ds_read_b128 v[236:239], v189 offset:26624
	ds_read_b128 v[248:251], v187 offset:26624
	ds_read_b128 v[252:255], v187 offset:28672
	s_waitcnt lgkmcnt(9)
	v_mfma_f32_32x32x16_bf16 v[114:129], v[208:211], v[190:193], v[114:129]
	s_waitcnt lgkmcnt(8)
	v_mfma_f32_32x32x16_bf16 v[98:113], v[208:211], v[212:215], v[98:113]
	ds_read_b128 v[208:211], v187 offset:30720
	s_waitcnt lgkmcnt(8)
	v_mfma_f32_32x32x16_bf16 v[82:97], v[216:219], v[190:193], v[82:97]
	s_waitcnt lgkmcnt(8)
	v_mfma_f32_32x32x16_bf16 v[66:81], v[216:219], v[212:215], v[66:81]
	s_waitcnt vmcnt(11)
	ds_write_b128 v185, v[130:133] offset:0
	s_waitcnt lgkmcnt(8)
	v_mfma_f32_32x32x16_bf16 v[50:65], v[220:223], v[190:193], v[50:65]
	s_waitcnt lgkmcnt(8)
	v_mfma_f32_32x32x16_bf16 v[34:49], v[220:223], v[212:215], v[34:49]
	s_waitcnt vmcnt(10)
	ds_write_b128 v185, v[134:137] offset:4096
	s_waitcnt lgkmcnt(8)
	v_mfma_f32_32x32x16_bf16 v[18:33], v[224:227], v[190:193], v[18:33]
	s_waitcnt lgkmcnt(8)
	v_mfma_f32_32x32x16_bf16 v[2:17], v[224:227], v[212:215], v[2:17]
	s_waitcnt vmcnt(9)
	ds_write_b128 v185, v[138:141] offset:8192
	s_waitcnt lgkmcnt(7)
	v_mfma_f32_32x32x16_bf16 v[114:129], v[232:235], v[228:231], v[114:129]
	s_waitcnt lgkmcnt(6)
	v_mfma_f32_32x32x16_bf16 v[98:113], v[232:235], v[236:239], v[98:113]
	s_waitcnt vmcnt(8)
	ds_write_b128 v185, v[142:145] offset:12288
	s_waitcnt lgkmcnt(6)
	v_mfma_f32_32x32x16_bf16 v[82:97], v[248:251], v[228:231], v[82:97]
	s_waitcnt lgkmcnt(6)
	v_mfma_f32_32x32x16_bf16 v[66:81], v[248:251], v[236:239], v[66:81]
	s_waitcnt vmcnt(7)
	ds_write_b128 v185, v[146:149] offset:16384
	s_waitcnt lgkmcnt(6)
	v_mfma_f32_32x32x16_bf16 v[50:65], v[252:255], v[228:231], v[50:65]
	s_waitcnt lgkmcnt(6)
	v_mfma_f32_32x32x16_bf16 v[34:49], v[252:255], v[236:239], v[34:49]
	s_waitcnt vmcnt(6)
	ds_write_b128 v185, v[150:153] offset:20480
	s_waitcnt lgkmcnt(6)
	v_mfma_f32_32x32x16_bf16 v[18:33], v[208:211], v[228:231], v[18:33]
	s_waitcnt lgkmcnt(6)
	v_mfma_f32_32x32x16_bf16 v[2:17], v[208:211], v[236:239], v[2:17]
	s_waitcnt lgkmcnt(0)
	s_barrier
; #define MFMA32(a, b, c) __builtin_amdgcn_mfma_f32_32x32x16_bf16((a), (b), (c), 0, 0, 0)
; DI void gemm_kloop4(f32x16 (&acc)[4][2], const u16* __restrict__ A, int lda, const u16* __restrict__ B, int ldb, int K,
;                     char* smem) {
;     ...
; #pragma unroll 1
;   for (int kt = 0; kt < nk; ++kt) {
;     if (kt + 1 < nk) {
; #pragma unroll
;       for (int i = 0; i < 8; ++i) ra[i] = *(const u32x4*)(Ap + (size_t)(32 * i) * lda + (kt + 1) * 64);
; #pragma unroll
;       for (int i = 0; i < 4; ++i) rb[i] = *(const u32x4*)(Bp + (size_t)(32 * i) * ldb + (kt + 1) * 64);
;     }
;     __builtin_amdgcn_s_setprio(1);
; #pragma unroll
;     for (int s = 0; s < 4; ++s) {
;       const int ch = ((2 * s + h5) ^ sw) << 4;
;       const bf16x8 b0 = *(const bf16x8*)(smem + boff + ch);
;       const bf16x8 b1 = *(const bf16x8*)(smem + boff + 4096 + ch);
; #pragma unroll
;       for (int mt = 0; mt < 4; ++mt) {
;         const bf16x8 a = *(const bf16x8*)(smem + aoff + mt * 4096 + ch);
;         acc[mt][0] = MFMA32(a, b0, acc[mt][0]);
;         acc[mt][1] = MFMA32(a, b1, acc[mt][1]);
;       }
;     }
;     __builtin_amdgcn_s_setprio(0);
;     __syncthreads();
;     if (kt + 1 < nk) {
; #pragma unroll
;       for (int i = 0; i < 8; ++i) *(u32x4*)(smem + woff + i * 4096) = ra[i];
; #pragma unroll
;       for (int i = 0; i < 4; ++i) *(u32x4*)(smem + 32768 + woff + i * 4096) = rb[i];
;     }
;     __syncthreads();
;   }
	s_add_i32 s44, s44, 2
	s_cmp_lt_u32 s44, 30
	s_cbranch_scc1 .Lg_ffn1_loop
	ds_read_b128 v[190:193], v188 offset:0
	ds_read_b128 v[208:211], v186 offset:0
	ds_read_b128 v[212:215], v188 offset:2048
	ds_read_b128 v[216:219], v186 offset:2048
	ds_read_b128 v[220:223], v186 offset:4096
	ds_read_b128 v[224:227], v186 offset:6144
	ds_read_b128 v[228:231], v189 offset:0
	ds_read_b128 v[232:235], v187 offset:0
	ds_read_b128 v[236:239], v189 offset:2048
	ds_read_b128 v[248:251], v187 offset:2048
	ds_read_b128 v[252:255], v187 offset:4096
	s_waitcnt lgkmcnt(9)
	v_mfma_f32_32x32x16_bf16 v[114:129], v[208:211], v[190:193], v[114:129]
	s_waitcnt lgkmcnt(8)
	v_mfma_f32_32x32x16_bf16 v[98:113], v[208:211], v[212:215], v[98:113]
	ds_read_b128 v[208:211], v187 offset:6144
	s_waitcnt lgkmcnt(8)
	v_mfma_f32_32x32x16_bf16 v[82:97], v[216:219], v[190:193], v[82:97]
	s_waitcnt lgkmcnt(8)
	v_mfma_f32_32x32x16_bf16 v[66:81], v[216:219], v[212:215], v[66:81]
	s_waitcnt vmcnt(5)
	ds_write_b128 v185, v[154:157] offset:24576
	s_waitcnt lgkmcnt(8)
	v_mfma_f32_32x32x16_bf16 v[50:65], v[220:223], v[190:193], v[50:65]
	s_waitcnt lgkmcnt(8)
	v_mfma_f32_32x32x16_bf16 v[34:49], v[220:223], v[212:215], v[34:49]
	s_waitcnt vmcnt(4)
	ds_write_b128 v185, v[158:161] offset:28672
	s_waitcnt lgkmcnt(8)
	v_mfma_f32_32x32x16_bf16 v[18:33], v[224:227], v[190:193], v[18:33]
	s_waitcnt lgkmcnt(8)
	v_mfma_f32_32x32x16_bf16 v[2:17], v[224:227], v[212:215], v[2:17]
	s_waitcnt vmcnt(3)
	ds_write_b128 v185, v[162:165] offset:32768
	s_waitcnt lgkmcnt(7)
	v_mfma_f32_32x32x16_bf16 v[114:129], v[232:235], v[228:231], v[114:129]
	s_waitcnt lgkmcnt(6)
	v_mfma_f32_32x32x16_bf16 v[98:113], v[232:235], v[236:239], v[98:113]
	s_waitcnt vmcnt(2)
	ds_write_b128 v185, v[166:169] offset:36864
	s_waitcnt lgkmcnt(6)
	v_mfma_f32_32x32x16_bf16 v[82:97], v[248:251], v[228:231], v[82:97]
	s_waitcnt lgkmcnt(6)
	v_mfma_f32_32x32x16_bf16 v[66:81], v[248:251], v[236:239], v[66:81]
	s_waitcnt vmcnt(1)
	ds_write_b128 v185, v[170:173] offset:40960
	s_waitcnt lgkmcnt(6)
	v_mfma_f32_32x32x16_bf16 v[50:65], v[252:255], v[228:231], v[50:65]
	s_waitcnt lgkmcnt(6)
	v_mfma_f32_32x32x16_bf16 v[34:49], v[252:255], v[236:239], v[34:49]
	s_waitcnt vmcnt(0)
	ds_write_b128 v185, v[174:177] offset:45056
	s_waitcnt lgkmcnt(6)
	v_mfma_f32_32x32x16_bf16 v[18:33], v[208:211], v[228:231], v[18:33]
	s_waitcnt lgkmcnt(6)
	v_mfma_f32_32x32x16_bf16 v[2:17], v[208:211], v[236:239], v[2:17]
	s_waitcnt lgkmcnt(0)
	s_barrier
	ds_read_b128 v[190:193], v188 offset:24576
	ds_read_b128 v[208:211], v186 offset:24576
	ds_read_b128 v[212:215], v188 offset:26624
	ds_read_b128 v[216:219], v186 offset:26624
	ds_read_b128 v[220:223], v186 offset:28672
	ds_read_b128 v[224:227], v186 offset:30720
	ds_read_b128 v[228:231], v189 offset:24576
	ds_read_b128 v[232:235], v187 offset:24576
	ds_read_b128 v[236:239], v189 offset:26624
	ds_read_b128 v[248:251], v187 offset:26624
	ds_read_b128 v[252:255], v187 offset:28672
	s_waitcnt lgkmcnt(9)
	v_mfma_f32_32x32x16_bf16 v[114:129], v[208:211], v[190:193], v[114:129]
	s_waitcnt lgkmcnt(8)
	v_mfma_f32_32x32x16_bf16 v[98:113], v[208:211], v[212:215], v[98:113]
	ds_read_b128 v[208:211], v187 offset:30720
	s_waitcnt lgkmcnt(8)
	v_mfma_f32_32x32x16_bf16 v[82:97], v[216:219], v[190:193], v[82:97]
	s_waitcnt lgkmcnt(8)
	v_mfma_f32_32x32x16_bf16 v[66:81], v[216:219], v[212:215], v[66:81]
	s_waitcnt lgkmcnt(7)
	v_mfma_f32_32x32x16_bf16 v[50:65], v[220:223], v[190:193], v[50:65]
	s_waitcnt lgkmcnt(7)
	v_mfma_f32_32x32x16_bf16 v[34:49], v[220:223], v[212:215], v[34:49]
	s_waitcnt lgkmcnt(6)
	v_mfma_f32_32x32x16_bf16 v[18:33], v[224:227], v[190:193], v[18:33]
	s_waitcnt lgkmcnt(6)
	v_mfma_f32_32x32x16_bf16 v[2:17], v[224:227], v[212:215], v[2:17]
	s_waitcnt lgkmcnt(4)
	v_mfma_f32_32x32x16_bf16 v[114:129], v[232:235], v[228:231], v[114:129]
	s_waitcnt lgkmcnt(3)
	v_mfma_f32_32x32x16_bf16 v[98:113], v[232:235], v[236:239], v[98:113]
	s_waitcnt lgkmcnt(2)
	v_mfma_f32_32x32x16_bf16 v[82:97], v[248:251], v[228:231], v[82:97]
	s_waitcnt lgkmcnt(2)
	v_mfma_f32_32x32x16_bf16 v[66:81], v[248:251], v[236:239], v[66:81]
	s_waitcnt lgkmcnt(1)
	v_mfma_f32_32x32x16_bf16 v[50:65], v[252:255], v[228:231], v[50:65]
	s_waitcnt lgkmcnt(1)
	v_mfma_f32_32x32x16_bf16 v[34:49], v[252:255], v[236:239], v[34:49]
	s_waitcnt lgkmcnt(0)
	v_mfma_f32_32x32x16_bf16 v[18:33], v[208:211], v[228:231], v[18:33]
	s_waitcnt lgkmcnt(0)
	v_mfma_f32_32x32x16_bf16 v[2:17], v[208:211], v[236:239], v[2:17]
	s_branch .LBB0_60
